# grid barrier rewritten: per-XCD last-arriver election (1 returning atomic), leader does wbl2 then adds nloc to 16 per-XCD release counters, every WG polls its own XCD counter; old two-level XSUB/TOP/T
# speedup vs baseline: 1.0052x; 1.0003x over previous
; #define LAS __attribute__((address_space(3)))
; DI unsigned xb_add(unsigned* p, unsigned v) { return __hip_atomic_fetch_add(p, v, __ATOMIC_RELAXED, __HIP_MEMORY_SCOPE_AGENT); }
; DI unsigned xb_xcc_id() { return (unsigned)__builtin_amdgcn_s_getreg((3 << 11) | 20) & 0xFu; }
; DI XcdBarrier xcd_barrier_post(unsigned* bar, volatile LAS unsigned* st) {
;   XcdBarrier b; b.bar = bar; b.x = xb_xcc_id(); b.st = st;
;   if (threadIdx.x == 0) (void)xb_add(&bar[XB_XCNT(b.x)], 1u);
;   return b;
; }
; __global__ void __launch_bounds__(256, 2) fwd_megakernel(Params p) {
;   __shared__ __attribute__((aligned(16))) char smem[SMEM_TOTAL];
;   unsigned* bar = (unsigned*)launder(p.ws);
;   unsigned* qcnt = (unsigned*)(launder(p.ws) + W_QCNT);
;   if (threadIdx.x < 4) ((volatile unsigned*)(smem + SMEM_MAIN))[threadIdx.x] = 0u;
;   __syncthreads();
;   (void)xcd_barrier_post(bar, (volatile LAS unsigned*)(smem + SMEM_MAIN));
.LBB0_2:
	s_or_b64 exec, exec, s[0:1]
	s_waitcnt lgkmcnt(0)
	v_writelane_b32 v226, s48, 47
	v_writelane_b32 v226, s49, 48
	v_writelane_b32 v226, 0, 46
	s_barrier
	s_getreg_b32 s8, hwreg(HW_REG_XCC_ID, 0, 4)
	v_cmp_eq_u32_e64 s[4:5], 0, v202
	v_mov_b64_e32 v[34:35], s[48:49]
	s_and_saveexec_b64 s[0:1], s[4:5]
	s_cbranch_execz .LBB0_6
	s_mov_b64 s[6:7], exec
	v_mbcnt_lo_u32_b32 v1, s6, 0
	v_mbcnt_hi_u32_b32 v1, s7, v1
	v_cmp_eq_u32_e32 vcc, 0, v1
	v_mov_b64_e32 v[34:35], s[48:49]
	s_and_saveexec_b64 s[2:3], vcc
	s_cbranch_execz .LBB0_5
	s_lshl_b32 s8, s8, 8
	s_and_b32 s8, s8, 0xf00
	s_bcnt1_i32_b64 s6, s[6:7]
	v_mov_b32_e32 v1, s8
	v_mov_b32_e32 v2, s6
	global_atomic_add v1, v2, s[48:49] offset:1024
	v_mov_b64_e32 v[34:35], s[48:49]

;   const int nkt = K / 64, nnt = Npad / 64;
;   const int b0 = (int)((blockIdx.x + gridDim.x - (unsigned)rot % gridDim.x) % gridDim.x);
;   for (int i = b0; i < nkt * nnt; i += gridDim.x) tr_tile(src, N, N, gain, dst, K, i % nkt, i / nkt, (float*)smem);
; __global__ void __launch_bounds__(256, 2) fwd_megakernel(Params p) {
;     ...
;   convert_weight(p.in[I_WIN0], 1024, 1216, 1280, p.in[I_LMPRE], (u16*)(launder(p.ws) + W_IN0T), smem);
.LBB0_6:
	s_or_b64 exec, exec, s[0:1]
	s_load_dword s50, s[54:55], 0x1f0
	s_add_u32 s0, s54, 0x1f0
	s_addc_u32 s1, s55, 0
	v_writelane_b32 v226, s0, 0
	s_waitcnt lgkmcnt(0)
	v_writelane_b32 v226, s50, 49
	v_cvt_f32_u32_e32 v1, s50
	v_writelane_b32 v226, s1, 1
	s_sub_i32 s0, 0, s50
	s_add_i32 s20, s50, s78
	v_rcp_iflag_f32_e32 v1, v1
	s_nop 0
	v_mul_f32_e32 v1, 0x4f7ffffe, v1
	v_cvt_u32_f32_e32 v1, v1
	s_nop 0
	v_readfirstlane_b32 s1, v1
	s_mul_i32 s0, s0, s1
	s_mul_hi_u32 s0, s1, s0
	s_add_i32 s21, s1, s0
	s_mul_hi_u32 s0, s20, s21
	s_mul_i32 s0, s0, s50
	s_sub_i32 s0, s20, s0
	s_sub_i32 s1, s0, s50
	s_cmp_ge_u32 s0, s50
	s_cselect_b32 s0, s1, s0
	s_sub_i32 s1, s0, s50
	s_cmp_ge_u32 s0, s50
	s_cselect_b32 s58, s1, s0
	s_cmpk_gt_i32 s58, 0x13f
	s_cbranch_scc1 .LBB0_22
	s_load_dwordx2 s[0:1], s[54:55], 0x40
	s_load_dwordx2 s[2:3], s[54:55], 0x70
	s_mov_b64 s[6:7], 0x400000
	v_lshl_add_u64 v[18:19], v[34:35], 0, s[6:7]
	v_mov_b32_e32 v21, 0
	s_waitcnt lgkmcnt(0)
	s_cmp_lg_u64 s[0:1], 0
	s_cselect_b64 s[6:7], -1, 0
	v_cndmask_b32_e64 v1, 0, 1, s[6:7]
	s_lshl_b32 s14, s58, 6
	s_lshl_b32 s15, s50, 6
	s_movk_i32 s16, 0x1300
	v_cmp_ne_u32_e64 s[6:7], 1, v1
	s_movk_i32 s17, 0x104
	s_mov_b32 s18, s58
	s_branch .LBB0_9

; DI unsigned xb_ld(unsigned* p) { return __hip_atomic_load(p, __ATOMIC_RELAXED, __HIP_MEMORY_SCOPE_AGENT); }
; DI unsigned xb_add(unsigned* p, unsigned v) { return __hip_atomic_fetch_add(p, v, __ATOMIC_RELAXED, __HIP_MEMORY_SCOPE_AGENT); }
; #define XB_SPIN(cond, bar) do { unsigned _sp = 0; while (cond) { __builtin_amdgcn_s_sleep(1); \
;     if ((++_sp & 255u) == 0u) { if (xb_ld(&(bar)[XB_TMO])) break; if (_sp > XB_SPIN_CAP) { atomicAdd(&(bar)[XB_TMO], 1u); break; } } } } while (0)
; DI void xcd_barrier_complete(unsigned* bar, unsigned x, unsigned& nloc, unsigned& nx) {
;   const unsigned G = gridDim.x * gridDim.y * gridDim.z;
;   unsigned sum, cnt, mine, sp = 0u;
;   for (;;) {
;     sum = 0u; cnt = 0u; mine = 0u;
; #pragma unroll
;     for (unsigned j = 0; j < 16; ++j) { const unsigned c = xb_ld(&bar[XB_XCNT(j)]); sum += c; cnt += (c > 0u) ? 1u : 0u; mine = (j == x) ? c : mine; }
;     if (sum == G) break;
;     __builtin_amdgcn_s_sleep(1);
;     if ((++sp & 255u) == 0u) { if (xb_ld(&bar[XB_TMO])) break; if (sp > XB_SPIN_CAP) { atomicAdd(&bar[XB_TMO], 1u); break; } }
;   }
;   nloc = mine > 0u ? mine : 1u; nx = cnt > 0u ? cnt : 1u;
; }
; DI void xcd_barrier(const XcdBarrier& b) {
;   asm volatile("s_waitcnt vmcnt(0)" ::: "memory");
;   __syncthreads();
;   if (threadIdx.x == 0) {
;     unsigned* bar = b.bar;
;     __builtin_amdgcn_s_waitcnt(0);
;     unsigned nloc = b.st[0], nx = b.st[1];
;     if (nloc == 0u) { xcd_barrier_complete(bar, b.x, nloc, nx); b.st[0] = nloc; b.st[1] = nx; }
;     const unsigned old = xb_add(&bar[XB_XSUB(b.x)], 1u);
;     const unsigned gen = old / nloc;
;     if (old + 1u == (gen + 1u) * nloc) {
;       __builtin_amdgcn_fence(__ATOMIC_RELEASE, "agent");
;       asm volatile("s_waitcnt vmcnt(0)" ::: "memory");
;       const unsigned og = xb_add(&bar[XB_TOP], 1u);
;       const unsigned tg = og / nx;
;       if (og + 1u == (tg + 1u) * nx) xb_add(&bar[XB_TOPGEN], 1u);
;       else XB_SPIN(xb_ld(&bar[XB_TOPGEN]) == tg, bar);
;       __builtin_amdgcn_fence(__ATOMIC_ACQUIRE, "agent");
;       xb_add(&bar[XB_XGEN(b.x)], 1u);
;       asm volatile("s_waitcnt vmcnt(0)" ::: "memory");
;     } else {
;       XB_SPIN(xb_ld(&bar[XB_XGEN(b.x)]) == gen, bar);
;       __builtin_amdgcn_fence(__ATOMIC_ACQUIRE, "agent");
;       asm volatile("s_waitcnt vmcnt(0)" ::: "memory");
;     }
;   }
;   __syncthreads();
; }
.LBB0_117:
	s_getreg_b32 s2, hwreg(HW_REG_XCC_ID, 0, 4)
	s_waitcnt vmcnt(0)
	s_barrier
	s_and_saveexec_b64 s[0:1], s[4:5]
	s_cbranch_execz .LBB0_161
	v_readlane_b32 s98, v226, 47
	v_readlane_b32 s99, v226, 48
	v_readlane_b32 s101, v226, 49
	s_mov_b64 exec, 0xffff
	v_mbcnt_lo_u32_b32 v253, -1, 0
	v_lshlrev_b32_e32 v253, 8, v253
	v_add_u32_e32 v253, 0x400, v253
	s_mov_b32 s100, 0
.Lfb_boot:
	global_load_dword v254, v253, s[98:99] sc1
	s_add_u32 s100, s100, 1
	s_waitcnt vmcnt(0)
	v_add_u32_dpp v255, v254, v254 quad_perm:[1,0,3,2] row_mask:0xf bank_mask:0xf
	s_nop 1
	v_add_u32_dpp v255, v255, v255 quad_perm:[2,3,0,1] row_mask:0xf bank_mask:0xf
	s_nop 1
	v_add_u32_dpp v255, v255, v255 row_half_mirror row_mask:0xf bank_mask:0xf
	s_nop 1
	v_add_u32_dpp v255, v255, v255 row_mirror row_mask:0xf bank_mask:0xf
	s_nop 1
	v_readfirstlane_b32 vcc_lo, v255
	s_cmp_eq_u32 vcc_lo, s101
	s_cbranch_scc1 .Lfb_bootdone
	s_cmpk_lt_u32 s100, 0x1000
	s_cbranch_scc0 .Lfb_bootdone
	s_sleep 1
	s_branch .Lfb_boot
.Lfb_bootdone:
	s_getreg_b32 vcc_lo, hwreg(HW_REG_XCC_ID, 0, 4)
	s_nop 3
	v_readlane_b32 vcc_hi, v254, vcc_lo
	s_nop 3
	v_writelane_b32 v226, vcc_hi, 50
	s_mov_b64 exec, 1
	v_readlane_b32 s100, v226, 46
	v_readlane_b32 vcc_hi, v226, 50
	s_getreg_b32 vcc_lo, hwreg(HW_REG_XCC_ID, 0, 4)
	s_add_u32 s100, s100, 1
	s_lshl_b32 vcc_lo, vcc_lo, 8
	v_writelane_b32 v226, s100, 46
	s_add_u32 vcc_lo, vcc_lo, 0x1400
	s_mul_i32 s101, s101, s100
	s_mul_i32 s100, vcc_hi, s100
	v_mov_b32_e32 v253, vcc_lo
	v_mov_b32_e32 v254, 1
	global_atomic_add v254, v253, v254, s[98:99] sc0
	v_add_u32_e32 v253, 0x1000, v253
	s_waitcnt vmcnt(0)
	v_readfirstlane_b32 vcc_lo, v254
	s_add_u32 vcc_lo, vcc_lo, 1
	s_cmp_lg_u32 vcc_lo, s100
	s_cbranch_scc1 .Lfb_poll_0
	buffer_wbl2 sc1
	s_waitcnt vmcnt(0)
	s_mov_b64 exec, 0xffff
	v_mbcnt_lo_u32_b32 v255, -1, 0
	v_mov_b32_e32 v254, vcc_hi
	v_lshlrev_b32_e32 v255, 8, v255
	v_add_u32_e32 v255, 0x2400, v255
	global_atomic_add v255, v254, s[98:99]
	s_mov_b64 exec, 1
.Lfb_poll_0:
	s_mov_b32 vcc_lo, 0
.Lfb_loop_0:
	global_load_dword v254, v253, s[98:99] sc1
	s_add_u32 vcc_lo, vcc_lo, 1
	s_waitcnt vmcnt(0)
	v_readfirstlane_b32 vcc_hi, v254
	s_cmp_ge_u32 vcc_hi, s101
	s_cbranch_scc1 .Lfb_done_0
	s_cmpk_lt_u32 vcc_lo, 0x1000
	s_cbranch_scc0 .Lfb_done_0
	s_sleep 1
	s_branch .Lfb_loop_0
.Lfb_done_0:
	buffer_inv sc1

; DI unsigned xb_ld(unsigned* p) { return __hip_atomic_load(p, __ATOMIC_RELAXED, __HIP_MEMORY_SCOPE_AGENT); }
; DI unsigned xb_add(unsigned* p, unsigned v) { return __hip_atomic_fetch_add(p, v, __ATOMIC_RELAXED, __HIP_MEMORY_SCOPE_AGENT); }
; #define XB_SPIN(cond, bar) do { unsigned _sp = 0; while (cond) { __builtin_amdgcn_s_sleep(1); \
;     if ((++_sp & 255u) == 0u) { if (xb_ld(&(bar)[XB_TMO])) break; if (_sp > XB_SPIN_CAP) { atomicAdd(&(bar)[XB_TMO], 1u); break; } } } } while (0)
; DI void xcd_barrier(const XcdBarrier& b) {
;   asm volatile("s_waitcnt vmcnt(0)" ::: "memory");
;   __syncthreads();
;   if (threadIdx.x == 0) {
;     unsigned* bar = b.bar;
;     __builtin_amdgcn_s_waitcnt(0);
;     unsigned nloc = b.st[0], nx = b.st[1];
;     if (nloc == 0u) { xcd_barrier_complete(bar, b.x, nloc, nx); b.st[0] = nloc; b.st[1] = nx; }
;     const unsigned old = xb_add(&bar[XB_XSUB(b.x)], 1u);
;     const unsigned gen = old / nloc;
;     if (old + 1u == (gen + 1u) * nloc) {
;       __builtin_amdgcn_fence(__ATOMIC_RELEASE, "agent");
;       asm volatile("s_waitcnt vmcnt(0)" ::: "memory");
;       const unsigned og = xb_add(&bar[XB_TOP], 1u);
;       const unsigned tg = og / nx;
;       if (og + 1u == (tg + 1u) * nx) xb_add(&bar[XB_TOPGEN], 1u);
;       else XB_SPIN(xb_ld(&bar[XB_TOPGEN]) == tg, bar);
;       __builtin_amdgcn_fence(__ATOMIC_ACQUIRE, "agent");
;       xb_add(&bar[XB_XGEN(b.x)], 1u);
;       asm volatile("s_waitcnt vmcnt(0)" ::: "memory");
;     } else {
;       XB_SPIN(xb_ld(&bar[XB_XGEN(b.x)]) == gen, bar);
;       __builtin_amdgcn_fence(__ATOMIC_ACQUIRE, "agent");
;       asm volatile("s_waitcnt vmcnt(0)" ::: "memory");
;     }
;   }
;   __syncthreads();
; }
.LBB0_425:
	s_getreg_b32 s6, hwreg(HW_REG_XCC_ID, 0, 4)
	s_waitcnt vmcnt(0)
	s_barrier
	s_and_saveexec_b64 s[0:1], s[4:5]
	s_cbranch_execz .LBB0_477
	v_readlane_b32 s98, v226, 47
	v_readlane_b32 s99, v226, 48
	v_readlane_b32 s101, v226, 49
	v_readlane_b32 s100, v226, 46
	v_readlane_b32 vcc_hi, v226, 50
	s_getreg_b32 vcc_lo, hwreg(HW_REG_XCC_ID, 0, 4)
	s_add_u32 s100, s100, 1
	s_lshl_b32 vcc_lo, vcc_lo, 8
	v_writelane_b32 v226, s100, 46
	s_add_u32 vcc_lo, vcc_lo, 0x1400
	s_mul_i32 s101, s101, s100
	s_mul_i32 s100, vcc_hi, s100
	v_mov_b32_e32 v253, vcc_lo
	v_mov_b32_e32 v254, 1
	global_atomic_add v254, v253, v254, s[98:99] sc0
	v_add_u32_e32 v253, 0x1000, v253
	s_waitcnt vmcnt(0)
	v_readfirstlane_b32 vcc_lo, v254
	s_add_u32 vcc_lo, vcc_lo, 1
	s_cmp_lg_u32 vcc_lo, s100
	s_cbranch_scc1 .Lfb_poll_1
	buffer_wbl2 sc1
	s_waitcnt vmcnt(0)
	s_mov_b64 exec, 0xffff
	v_mbcnt_lo_u32_b32 v255, -1, 0
	v_mov_b32_e32 v254, vcc_hi
	v_lshlrev_b32_e32 v255, 8, v255
	v_add_u32_e32 v255, 0x2400, v255
	global_atomic_add v255, v254, s[98:99]
	s_mov_b64 exec, 1

; DI unsigned xb_ld(unsigned* p) { return __hip_atomic_load(p, __ATOMIC_RELAXED, __HIP_MEMORY_SCOPE_AGENT); }
; DI unsigned xb_add(unsigned* p, unsigned v) { return __hip_atomic_fetch_add(p, v, __ATOMIC_RELAXED, __HIP_MEMORY_SCOPE_AGENT); }
; #define XB_SPIN(cond, bar) do { unsigned _sp = 0; while (cond) { __builtin_amdgcn_s_sleep(1); \
;     if ((++_sp & 255u) == 0u) { if (xb_ld(&(bar)[XB_TMO])) break; if (_sp > XB_SPIN_CAP) { atomicAdd(&(bar)[XB_TMO], 1u); break; } } } } while (0)
; DI void xcd_barrier(const XcdBarrier& b) {
;   asm volatile("s_waitcnt vmcnt(0)" ::: "memory");
;   __syncthreads();
;   if (threadIdx.x == 0) {
;     unsigned* bar = b.bar;
;     __builtin_amdgcn_s_waitcnt(0);
;     unsigned nloc = b.st[0], nx = b.st[1];
;     if (nloc == 0u) { xcd_barrier_complete(bar, b.x, nloc, nx); b.st[0] = nloc; b.st[1] = nx; }
;     const unsigned old = xb_add(&bar[XB_XSUB(b.x)], 1u);
;     const unsigned gen = old / nloc;
;     if (old + 1u == (gen + 1u) * nloc) {
;       __builtin_amdgcn_fence(__ATOMIC_RELEASE, "agent");
;       asm volatile("s_waitcnt vmcnt(0)" ::: "memory");
;       const unsigned og = xb_add(&bar[XB_TOP], 1u);
;       const unsigned tg = og / nx;
;       if (og + 1u == (tg + 1u) * nx) xb_add(&bar[XB_TOPGEN], 1u);
;       else XB_SPIN(xb_ld(&bar[XB_TOPGEN]) == tg, bar);
;       __builtin_amdgcn_fence(__ATOMIC_ACQUIRE, "agent");
;       xb_add(&bar[XB_XGEN(b.x)], 1u);
;       asm volatile("s_waitcnt vmcnt(0)" ::: "memory");
;     } else {
;       XB_SPIN(xb_ld(&bar[XB_XGEN(b.x)]) == gen, bar);
;       __builtin_amdgcn_fence(__ATOMIC_ACQUIRE, "agent");
;       asm volatile("s_waitcnt vmcnt(0)" ::: "memory");
;     }
;   }
;   __syncthreads();
; }
.LBB0_499:
	s_or_b64 exec, exec, s[0:1]
	s_getreg_b32 s2, hwreg(HW_REG_XCC_ID, 0, 4)
	s_waitcnt vmcnt(0)
	s_barrier
	s_and_saveexec_b64 s[0:1], s[4:5]
	s_cbranch_execz .LBB0_543
	v_readlane_b32 s98, v226, 47
	v_readlane_b32 s99, v226, 48
	v_readlane_b32 s101, v226, 49
	v_readlane_b32 s100, v226, 46
	v_readlane_b32 vcc_hi, v226, 50
	s_getreg_b32 vcc_lo, hwreg(HW_REG_XCC_ID, 0, 4)
	s_add_u32 s100, s100, 1
	s_lshl_b32 vcc_lo, vcc_lo, 8
	v_writelane_b32 v226, s100, 46
	s_add_u32 vcc_lo, vcc_lo, 0x1400
	s_mul_i32 s101, s101, s100
	s_mul_i32 s100, vcc_hi, s100
	v_mov_b32_e32 v253, vcc_lo
	v_mov_b32_e32 v254, 1
	global_atomic_add v254, v253, v254, s[98:99] sc0
	v_add_u32_e32 v253, 0x1000, v253
	s_waitcnt vmcnt(0)
	v_readfirstlane_b32 vcc_lo, v254
	s_add_u32 vcc_lo, vcc_lo, 1
	s_cmp_lg_u32 vcc_lo, s100
	s_cbranch_scc1 .Lfb_poll_2
	buffer_wbl2 sc1
	s_waitcnt vmcnt(0)
	s_mov_b64 exec, 0xffff
	v_mbcnt_lo_u32_b32 v255, -1, 0
	v_mov_b32_e32 v254, vcc_hi
	v_lshlrev_b32_e32 v255, 8, v255
	v_add_u32_e32 v255, 0x2400, v255
	global_atomic_add v255, v254, s[98:99]
	s_mov_b64 exec, 1

; __global__ void __launch_bounds__(256, 2) fwd_megakernel(Params p) {
;     ...
;   for (int g = 0; g < 2; g++) {
;     {
;       const u16* cqn = (const u16*)(launder(p.ws) + W_CQN);
;       const u16* wuqT = (const u16*)(launder(p.ws) + W_UQT);
;       const u16* latall = (const u16*)(launder(p.ws) + W_LATALL);
;       const u16* lats = latall + (long)NP * 256;
;       const u16* wukT = (const u16*)(launder(p.ws) + W_UKT);
;       const u16* wuvT = (const u16*)(launder(p.ws) + W_UVT);
;       const u16* wukTg = wukT + (long)g * 512 * 256;
;       const u16* wuvTg = wuvT + (long)g * 512 * 256;
;       const float* ct = (const float*)(launder(p.ws) + W_ROPE);
;       const float* st = ct + 16384 * 32;
;       u16* Q = (u16*)(launder(p.ws) + W_Q);
;       u16* knp = (u16*)(launder(p.ws) + W_KNP);
;       u16* vtp = (u16*)(launder(p.ws) + W_VTP);
;       u16* kns = (u16*)(launder(p.ws) + W_KNS);
;       u16* vts = (u16*)(launder(p.ws) + W_VTS);
;       const int n_q = (g == 0) ? (NT / 128) * 12 : 0;
;       const int n_kp = (g == 0) ? (NP / 128) * 8 : 0, n_vp = n_kp;
;       const int n_ks = (NSKV / 128) * 4, n_vs = n_ks;
;       const int e1 = n_q, e2 = e1 + n_kp, e3 = e2 + n_vp, e4 = e3 + n_ks, e5 = e4 + n_vs;
;       for (int t = blockIdx.x; t < e5; t += gridDim.x) {
.LBB0_543:
	v_writelane_b32 v226, s60, 8
	s_nop 1
	v_writelane_b32 v226, s61, 9
	v_writelane_b32 v226, s62, 10
	v_writelane_b32 v226, s63, 11
	v_writelane_b32 v226, s58, 12
	v_writelane_b32 v226, s57, 13
	v_writelane_b32 v226, s56, 14
	v_writelane_b32 v226, s54, 15
	s_nop 1
	v_writelane_b32 v226, s55, 16
	s_or_b64 exec, exec, s[0:1]
	s_add_u32 s0, s48, 0x4000
	v_writelane_b32 v226, s0, 17
	s_addc_u32 s0, s49, 0
	s_add_u32 s20, s48, 0x11900000
	s_addc_u32 s21, s49, 0
	s_add_u32 s22, s48, 0x680000
	s_addc_u32 s23, s49, 0
	s_add_u32 s24, s48, 0x3900000
	s_addc_u32 s25, s49, 0
	v_writelane_b32 v226, s0, 18
	s_add_u32 s0, s48, 0x4100000
	s_addc_u32 s1, s49, 0
	s_add_u32 s28, s48, 0x7c0000
	v_writelane_b32 v226, s0, 19
	s_addc_u32 s29, s49, 0
	s_mov_b64 s[16:17], src_shared_base
	v_writelane_b32 v226, s1, 20
	s_add_u32 s0, s48, 0x840000
	s_addc_u32 s1, s49, 0
	s_add_u32 s34, s48, 0x1000000
	s_addc_u32 s35, s49, 0
	s_add_u32 s36, s48, 0x1200000
	s_addc_u32 s37, s49, 0
	s_add_u32 s38, s48, 0xe300000
	s_addc_u32 s39, s49, 0
	s_add_u32 s40, s48, 0x6900000
	s_addc_u32 s41, s49, 0
	s_add_u32 s42, s48, 0x8900000
	s_addc_u32 s43, s49, 0
	s_add_u32 s58, s48, 0xa900000
	s_addc_u32 s59, s49, 0
	s_add_u32 s60, s48, 0x1500000
	s_addc_u32 s61, s49, 0
	s_add_u32 s62, s48, 0x200
	s_addc_u32 s63, s49, 0
	s_add_u32 s64, s48, 0x1000
	s_addc_u32 s65, s49, 0
	s_add_u32 s66, s48, 0x1100
	s_addc_u32 s67, s49, 0
	s_add_u32 s68, s48, 0x1200
	s_addc_u32 s69, s49, 0
	s_add_u32 s70, s48, 0x1300
	v_writelane_b32 v226, s0, 21
	s_addc_u32 s71, s49, 0
	s_movk_i32 s16, 0x80
	v_writelane_b32 v226, s1, 22
	s_add_u32 s0, s48, 0x3400
	s_addc_u32 s1, s49, 0
	v_writelane_b32 v226, s0, 23
	s_mov_b64 s[18:19], 0x4000
	v_cmp_gt_u32_e64 s[6:7], s16, v202
	v_writelane_b32 v226, s1, 24
	s_add_u32 s0, s48, 0x3500
	s_addc_u32 s1, s49, 0
	s_add_u32 s76, s48, 0x5200000
	v_writelane_b32 v226, s0, 25
	s_addc_u32 s77, s49, 0
	s_mov_b64 s[8:9], -1
	v_writelane_b32 v226, s1, 26
	s_add_u32 s0, s48, 0xd100000
	s_addc_u32 s1, s49, 0
	v_writelane_b32 v226, s0, 27
	s_movk_i32 s51, 0x110
	v_mov_b32_e32 v1, 0
	v_writelane_b32 v226, s1, 28
	s_add_u32 s0, s48, 0x300000
	s_addc_u32 s1, s49, 0
	v_writelane_b32 v226, s0, 29
	s_movk_i32 s33, 0x4000
	s_mov_b64 s[88:89], 0x8000
	v_writelane_b32 v226, s1, 30
	s_add_u32 s0, s48, 0x380000
	s_addc_u32 s1, s49, 0
	v_writelane_b32 v226, s0, 31
	s_mov_b32 s80, 0x8000
	s_mov_b32 s81, 0xc000
	v_writelane_b32 v226, s1, 32
	s_add_u32 s0, s48, 0x5900000
	s_addc_u32 s1, s49, 0
	v_writelane_b32 v226, s0, 33
	s_movk_i32 s82, 0x90
	s_mov_b32 s83, 0xfffffc0
	v_writelane_b32 v226, s1, 34
	s_add_u32 s0, s48, 0x6100000
	s_addc_u32 s1, s49, 0
	v_writelane_b32 v226, s0, 35
	s_movk_i32 s84, 0x300
	s_movk_i32 s85, 0xc00
	v_writelane_b32 v226, s1, 36
	s_lshl_b32 s0, s78, 7
	v_writelane_b32 v226, s0, 37
	s_or_b32 s0, s0, 0x60
	v_mov_b32_e32 v205, 0x12000
	v_mov_b32_e32 v206, 0x12004
	v_mov_b32_e32 v207, 0x1000
	v_mov_b32_e32 v208, 0x2000
	v_mov_b32_e32 v209, 1
	s_movk_i32 s86, 0xffe0
	s_movk_i32 s44, 0x190
	s_movk_i32 s45, 0xfef8
	s_movk_i32 s46, 0x2000
	s_movk_i32 s47, 0x3000
	v_mov_b32_e32 v210, 0x400
	v_mov_b32_e32 v184, 0x12010
	v_mov_b32_e32 v185, s17
	v_mov_b32_e32 v211, 0x4000
	v_mbcnt_hi_u32_b32 v203, -1, v204
	s_mov_b64 s[90:91], 0xc000
	s_mov_b64 s[92:93], 0x80
	s_mov_b64 s[94:95], 0x10000
	s_mov_b32 s10, 0
	s_mov_b32 s12, 0
	s_waitcnt lgkmcnt(0)
	s_barrier
	v_writelane_b32 v226, s0, 38
	s_branch .LBB0_546
.LBB0_545:
	s_or_b64 exec, exec, s[0:1]
	s_mov_b32 s10, 1
	s_mov_b64 s[8:9], 0
	s_and_b64 vcc, exec, s[96:97]
	s_waitcnt lgkmcnt(0)
	s_barrier
	s_cbranch_vccnz .LBB0_758

; DI unsigned xb_ld(unsigned* p) { return __hip_atomic_load(p, __ATOMIC_RELAXED, __HIP_MEMORY_SCOPE_AGENT); }
; DI unsigned xb_add(unsigned* p, unsigned v) { return __hip_atomic_fetch_add(p, v, __ATOMIC_RELAXED, __HIP_MEMORY_SCOPE_AGENT); }
; #define XB_SPIN(cond, bar) do { unsigned _sp = 0; while (cond) { __builtin_amdgcn_s_sleep(1); \
;     if ((++_sp & 255u) == 0u) { if (xb_ld(&(bar)[XB_TMO])) break; if (_sp > XB_SPIN_CAP) { atomicAdd(&(bar)[XB_TMO], 1u); break; } } } } while (0)
; DI void xcd_barrier(const XcdBarrier& b) {
;   asm volatile("s_waitcnt vmcnt(0)" ::: "memory");
;   __syncthreads();
;   if (threadIdx.x == 0) {
;     unsigned* bar = b.bar;
;     __builtin_amdgcn_s_waitcnt(0);
;     unsigned nloc = b.st[0], nx = b.st[1];
;     if (nloc == 0u) { xcd_barrier_complete(bar, b.x, nloc, nx); b.st[0] = nloc; b.st[1] = nx; }
;     const unsigned old = xb_add(&bar[XB_XSUB(b.x)], 1u);
;     const unsigned gen = old / nloc;
;     if (old + 1u == (gen + 1u) * nloc) {
;       __builtin_amdgcn_fence(__ATOMIC_RELEASE, "agent");
;       asm volatile("s_waitcnt vmcnt(0)" ::: "memory");
;       const unsigned og = xb_add(&bar[XB_TOP], 1u);
;       const unsigned tg = og / nx;
;       if (og + 1u == (tg + 1u) * nx) xb_add(&bar[XB_TOPGEN], 1u);
;       else XB_SPIN(xb_ld(&bar[XB_TOPGEN]) == tg, bar);
;       __builtin_amdgcn_fence(__ATOMIC_ACQUIRE, "agent");
;       xb_add(&bar[XB_XGEN(b.x)], 1u);
;       asm volatile("s_waitcnt vmcnt(0)" ::: "memory");
;     } else {
;       XB_SPIN(xb_ld(&bar[XB_XGEN(b.x)]) == gen, bar);
;       __builtin_amdgcn_fence(__ATOMIC_ACQUIRE, "agent");
;       asm volatile("s_waitcnt vmcnt(0)" ::: "memory");
;     }
;   }
;   __syncthreads();
; }
.LBB0_569:
	s_getreg_b32 s2, hwreg(HW_REG_XCC_ID, 0, 4)
	s_waitcnt vmcnt(0)
	s_waitcnt vmcnt(63) expcnt(7) lgkmcnt(15)
	s_barrier
	s_and_saveexec_b64 s[0:1], s[4:5]
	s_cbranch_execz .LBB0_621
	v_readlane_b32 s98, v226, 47
	v_readlane_b32 s99, v226, 48
	v_readlane_b32 s101, v226, 49
	v_readlane_b32 s100, v226, 46
	v_readlane_b32 vcc_hi, v226, 50
	s_getreg_b32 vcc_lo, hwreg(HW_REG_XCC_ID, 0, 4)
	s_add_u32 s100, s100, 1
	s_lshl_b32 vcc_lo, vcc_lo, 8
	v_writelane_b32 v226, s100, 46
	s_add_u32 vcc_lo, vcc_lo, 0x1400
	s_mul_i32 s101, s101, s100
	s_mul_i32 s100, vcc_hi, s100
	v_mov_b32_e32 v253, vcc_lo
	v_mov_b32_e32 v254, 1
	global_atomic_add v254, v253, v254, s[98:99] sc0
	v_add_u32_e32 v253, 0x1000, v253
	s_waitcnt vmcnt(0)
	v_readfirstlane_b32 vcc_lo, v254
	s_add_u32 vcc_lo, vcc_lo, 1
	s_cmp_lg_u32 vcc_lo, s100
	s_cbranch_scc1 .Lfb_poll_3
	buffer_wbl2 sc1
	s_waitcnt vmcnt(0)
	s_mov_b64 exec, 0xffff
	v_mbcnt_lo_u32_b32 v255, -1, 0
	v_mov_b32_e32 v254, vcc_hi
	v_lshlrev_b32_e32 v255, 8, v255
	v_add_u32_e32 v255, 0x2400, v255
	global_atomic_add v255, v254, s[98:99]
	s_mov_b64 exec, 1

; DI unsigned xb_ld(unsigned* p) { return __hip_atomic_load(p, __ATOMIC_RELAXED, __HIP_MEMORY_SCOPE_AGENT); }
; DI unsigned xb_add(unsigned* p, unsigned v) { return __hip_atomic_fetch_add(p, v, __ATOMIC_RELAXED, __HIP_MEMORY_SCOPE_AGENT); }
; #define XB_SPIN(cond, bar) do { unsigned _sp = 0; while (cond) { __builtin_amdgcn_s_sleep(1); \
;     if ((++_sp & 255u) == 0u) { if (xb_ld(&(bar)[XB_TMO])) break; if (_sp > XB_SPIN_CAP) { atomicAdd(&(bar)[XB_TMO], 1u); break; } } } } while (0)
; DI void xcd_barrier(const XcdBarrier& b) {
;     ...
;     __builtin_amdgcn_s_waitcnt(0);
;     unsigned nloc = b.st[0], nx = b.st[1];
;     if (nloc == 0u) { xcd_barrier_complete(bar, b.x, nloc, nx); b.st[0] = nloc; b.st[1] = nx; }
;     const unsigned old = xb_add(&bar[XB_XSUB(b.x)], 1u);
;     const unsigned gen = old / nloc;
;     if (old + 1u == (gen + 1u) * nloc) {
;       __builtin_amdgcn_fence(__ATOMIC_RELEASE, "agent");
;       asm volatile("s_waitcnt vmcnt(0)" ::: "memory");
;       const unsigned og = xb_add(&bar[XB_TOP], 1u);
;       const unsigned tg = og / nx;
;       if (og + 1u == (tg + 1u) * nx) xb_add(&bar[XB_TOPGEN], 1u);
;       else XB_SPIN(xb_ld(&bar[XB_TOPGEN]) == tg, bar);
;       __builtin_amdgcn_fence(__ATOMIC_ACQUIRE, "agent");
;       xb_add(&bar[XB_XGEN(b.x)], 1u);
;       asm volatile("s_waitcnt vmcnt(0)" ::: "memory");
;     } else {
;       XB_SPIN(xb_ld(&bar[XB_XGEN(b.x)]) == gen, bar);
;       __builtin_amdgcn_fence(__ATOMIC_ACQUIRE, "agent");
;       asm volatile("s_waitcnt vmcnt(0)" ::: "memory");
;     }
;   }
.Lfb_done_3:
	buffer_inv sc1
	s_branch .LBB0_621

; DI unsigned xb_ld(unsigned* p) { return __hip_atomic_load(p, __ATOMIC_RELAXED, __HIP_MEMORY_SCOPE_AGENT); }
; DI unsigned xb_add(unsigned* p, unsigned v) { return __hip_atomic_fetch_add(p, v, __ATOMIC_RELAXED, __HIP_MEMORY_SCOPE_AGENT); }
; #define XB_SPIN(cond, bar) do { unsigned _sp = 0; while (cond) { __builtin_amdgcn_s_sleep(1); \
;     if ((++_sp & 255u) == 0u) { if (xb_ld(&(bar)[XB_TMO])) break; if (_sp > XB_SPIN_CAP) { atomicAdd(&(bar)[XB_TMO], 1u); break; } } } } while (0)
; DI void xcd_barrier(const XcdBarrier& b) {
;   asm volatile("s_waitcnt vmcnt(0)" ::: "memory");
;   __syncthreads();
;   if (threadIdx.x == 0) {
;     unsigned* bar = b.bar;
;     __builtin_amdgcn_s_waitcnt(0);
;     unsigned nloc = b.st[0], nx = b.st[1];
;     if (nloc == 0u) { xcd_barrier_complete(bar, b.x, nloc, nx); b.st[0] = nloc; b.st[1] = nx; }
;     const unsigned old = xb_add(&bar[XB_XSUB(b.x)], 1u);
;     const unsigned gen = old / nloc;
;     if (old + 1u == (gen + 1u) * nloc) {
;       __builtin_amdgcn_fence(__ATOMIC_RELEASE, "agent");
;       asm volatile("s_waitcnt vmcnt(0)" ::: "memory");
;       const unsigned og = xb_add(&bar[XB_TOP], 1u);
;       const unsigned tg = og / nx;
;       if (og + 1u == (tg + 1u) * nx) xb_add(&bar[XB_TOPGEN], 1u);
;       else XB_SPIN(xb_ld(&bar[XB_TOPGEN]) == tg, bar);
;       __builtin_amdgcn_fence(__ATOMIC_ACQUIRE, "agent");
;       xb_add(&bar[XB_XGEN(b.x)], 1u);
;       asm volatile("s_waitcnt vmcnt(0)" ::: "memory");
;     } else {
;       XB_SPIN(xb_ld(&bar[XB_XGEN(b.x)]) == gen, bar);
;       __builtin_amdgcn_fence(__ATOMIC_ACQUIRE, "agent");
;       asm volatile("s_waitcnt vmcnt(0)" ::: "memory");
;     }
;   }
;   __syncthreads();
; }
.LBB0_707:
	s_or_b64 exec, exec, s[56:57]
	s_getreg_b32 s2, hwreg(HW_REG_XCC_ID, 0, 4)
	s_waitcnt vmcnt(0)
	s_barrier
	s_and_saveexec_b64 s[0:1], s[4:5]
	s_cbranch_execz .LBB0_545
	v_readlane_b32 s98, v226, 47
	v_readlane_b32 s99, v226, 48
	v_readlane_b32 s101, v226, 49
	v_readlane_b32 s100, v226, 46
	v_readlane_b32 vcc_hi, v226, 50
	s_getreg_b32 vcc_lo, hwreg(HW_REG_XCC_ID, 0, 4)
	s_add_u32 s100, s100, 1
	s_lshl_b32 vcc_lo, vcc_lo, 8
	v_writelane_b32 v226, s100, 46
	s_add_u32 vcc_lo, vcc_lo, 0x1400
	s_mul_i32 s101, s101, s100
	s_mul_i32 s100, vcc_hi, s100
	v_mov_b32_e32 v253, vcc_lo
	v_mov_b32_e32 v254, 1
	global_atomic_add v254, v253, v254, s[98:99] sc0
	v_add_u32_e32 v253, 0x1000, v253
	s_waitcnt vmcnt(0)
	v_readfirstlane_b32 vcc_lo, v254
	s_add_u32 vcc_lo, vcc_lo, 1
	s_cmp_lg_u32 vcc_lo, s100
	s_cbranch_scc1 .Lfb_poll_4
	buffer_wbl2 sc1
	s_waitcnt vmcnt(0)
	s_mov_b64 exec, 0xffff
	v_mbcnt_lo_u32_b32 v255, -1, 0
	v_mov_b32_e32 v254, vcc_hi
	v_lshlrev_b32_e32 v255, 8, v255
	v_add_u32_e32 v255, 0x2400, v255
	global_atomic_add v255, v254, s[98:99]
	s_mov_b64 exec, 1

; DI unsigned xb_ld(unsigned* p) { return __hip_atomic_load(p, __ATOMIC_RELAXED, __HIP_MEMORY_SCOPE_AGENT); }
; DI unsigned xb_add(unsigned* p, unsigned v) { return __hip_atomic_fetch_add(p, v, __ATOMIC_RELAXED, __HIP_MEMORY_SCOPE_AGENT); }
; #define XB_SPIN(cond, bar) do { unsigned _sp = 0; while (cond) { __builtin_amdgcn_s_sleep(1); \
;     if ((++_sp & 255u) == 0u) { if (xb_ld(&(bar)[XB_TMO])) break; if (_sp > XB_SPIN_CAP) { atomicAdd(&(bar)[XB_TMO], 1u); break; } } } } while (0)
; DI void xcd_barrier(const XcdBarrier& b) {
;   asm volatile("s_waitcnt vmcnt(0)" ::: "memory");
;   __syncthreads();
;   if (threadIdx.x == 0) {
;     unsigned* bar = b.bar;
;     __builtin_amdgcn_s_waitcnt(0);
;     unsigned nloc = b.st[0], nx = b.st[1];
;     if (nloc == 0u) { xcd_barrier_complete(bar, b.x, nloc, nx); b.st[0] = nloc; b.st[1] = nx; }
;     const unsigned old = xb_add(&bar[XB_XSUB(b.x)], 1u);
;     const unsigned gen = old / nloc;
;     if (old + 1u == (gen + 1u) * nloc) {
;       __builtin_amdgcn_fence(__ATOMIC_RELEASE, "agent");
;       asm volatile("s_waitcnt vmcnt(0)" ::: "memory");
;       const unsigned og = xb_add(&bar[XB_TOP], 1u);
;       const unsigned tg = og / nx;
;       if (og + 1u == (tg + 1u) * nx) xb_add(&bar[XB_TOPGEN], 1u);
;       else XB_SPIN(xb_ld(&bar[XB_TOPGEN]) == tg, bar);
;       __builtin_amdgcn_fence(__ATOMIC_ACQUIRE, "agent");
;       xb_add(&bar[XB_XGEN(b.x)], 1u);
;       asm volatile("s_waitcnt vmcnt(0)" ::: "memory");
;     } else {
;       XB_SPIN(xb_ld(&bar[XB_XGEN(b.x)]) == gen, bar);
;       __builtin_amdgcn_fence(__ATOMIC_ACQUIRE, "agent");
;       asm volatile("s_waitcnt vmcnt(0)" ::: "memory");
;     }
;   }
;   __syncthreads();
; }
.LBB0_849:
	s_getreg_b32 s2, hwreg(HW_REG_XCC_ID, 0, 4)
	s_waitcnt vmcnt(0)
	s_barrier
	s_and_saveexec_b64 s[0:1], s[4:5]
	s_cbranch_execz .LBB0_901
	v_readlane_b32 s98, v226, 47
	v_readlane_b32 s99, v226, 48
	v_readlane_b32 s101, v226, 49
	v_readlane_b32 s100, v226, 46
	v_readlane_b32 vcc_hi, v226, 50
	s_getreg_b32 vcc_lo, hwreg(HW_REG_XCC_ID, 0, 4)
	s_add_u32 s100, s100, 1
	s_lshl_b32 vcc_lo, vcc_lo, 8
	v_writelane_b32 v226, s100, 46
	s_add_u32 vcc_lo, vcc_lo, 0x1400
	s_mul_i32 s101, s101, s100
	s_mul_i32 s100, vcc_hi, s100
	v_mov_b32_e32 v253, vcc_lo
	v_mov_b32_e32 v254, 1
	global_atomic_add v254, v253, v254, s[98:99] sc0
	v_add_u32_e32 v253, 0x1000, v253
	s_waitcnt vmcnt(0)
	v_readfirstlane_b32 vcc_lo, v254
	s_add_u32 vcc_lo, vcc_lo, 1
	s_cmp_lg_u32 vcc_lo, s100
	s_cbranch_scc1 .Lfb_poll_5
	buffer_wbl2 sc1
	s_waitcnt vmcnt(0)
	s_mov_b64 exec, 0xffff
	v_mbcnt_lo_u32_b32 v255, -1, 0
	v_mov_b32_e32 v254, vcc_hi
	v_lshlrev_b32_e32 v255, 8, v255
	v_add_u32_e32 v255, 0x2400, v255
	global_atomic_add v255, v254, s[98:99]
	s_mov_b64 exec, 1

; DI unsigned xb_ld(unsigned* p) { return __hip_atomic_load(p, __ATOMIC_RELAXED, __HIP_MEMORY_SCOPE_AGENT); }
; DI unsigned xb_add(unsigned* p, unsigned v) { return __hip_atomic_fetch_add(p, v, __ATOMIC_RELAXED, __HIP_MEMORY_SCOPE_AGENT); }
; #define XB_SPIN(cond, bar) do { unsigned _sp = 0; while (cond) { __builtin_amdgcn_s_sleep(1); \
;     if ((++_sp & 255u) == 0u) { if (xb_ld(&(bar)[XB_TMO])) break; if (_sp > XB_SPIN_CAP) { atomicAdd(&(bar)[XB_TMO], 1u); break; } } } } while (0)
; DI void xcd_barrier(const XcdBarrier& b) {
;   asm volatile("s_waitcnt vmcnt(0)" ::: "memory");
;   __syncthreads();
;   if (threadIdx.x == 0) {
;     unsigned* bar = b.bar;
;     __builtin_amdgcn_s_waitcnt(0);
;     unsigned nloc = b.st[0], nx = b.st[1];
;     if (nloc == 0u) { xcd_barrier_complete(bar, b.x, nloc, nx); b.st[0] = nloc; b.st[1] = nx; }
;     const unsigned old = xb_add(&bar[XB_XSUB(b.x)], 1u);
;     const unsigned gen = old / nloc;
;     if (old + 1u == (gen + 1u) * nloc) {
;       __builtin_amdgcn_fence(__ATOMIC_RELEASE, "agent");
;       asm volatile("s_waitcnt vmcnt(0)" ::: "memory");
;       const unsigned og = xb_add(&bar[XB_TOP], 1u);
;       const unsigned tg = og / nx;
;       if (og + 1u == (tg + 1u) * nx) xb_add(&bar[XB_TOPGEN], 1u);
;       else XB_SPIN(xb_ld(&bar[XB_TOPGEN]) == tg, bar);
;       __builtin_amdgcn_fence(__ATOMIC_ACQUIRE, "agent");
;       xb_add(&bar[XB_XGEN(b.x)], 1u);
;       asm volatile("s_waitcnt vmcnt(0)" ::: "memory");
;     } else {
;       XB_SPIN(xb_ld(&bar[XB_XGEN(b.x)]) == gen, bar);
;       __builtin_amdgcn_fence(__ATOMIC_ACQUIRE, "agent");
;       asm volatile("s_waitcnt vmcnt(0)" ::: "memory");
;     }
;   }
;   __syncthreads();
; }
.LBB0_932:
	s_getreg_b32 s2, hwreg(HW_REG_XCC_ID, 0, 4)
	s_waitcnt vmcnt(0)
	s_waitcnt lgkmcnt(0)
	s_barrier
	s_and_saveexec_b64 s[0:1], s[4:5]
	s_cbranch_execz .LBB0_976
	v_readlane_b32 s98, v226, 47
	v_readlane_b32 s99, v226, 48
	v_readlane_b32 s101, v226, 49
	v_readlane_b32 s100, v226, 46
	v_readlane_b32 vcc_hi, v226, 50
	s_getreg_b32 vcc_lo, hwreg(HW_REG_XCC_ID, 0, 4)
	s_add_u32 s100, s100, 1
	s_lshl_b32 vcc_lo, vcc_lo, 8
	v_writelane_b32 v226, s100, 46
	s_add_u32 vcc_lo, vcc_lo, 0x1400
	s_mul_i32 s101, s101, s100
	s_mul_i32 s100, vcc_hi, s100
	v_mov_b32_e32 v253, vcc_lo
	v_mov_b32_e32 v254, 1
	global_atomic_add v254, v253, v254, s[98:99] sc0
	v_add_u32_e32 v253, 0x1000, v253
	s_waitcnt vmcnt(0)
	v_readfirstlane_b32 vcc_lo, v254
	s_add_u32 vcc_lo, vcc_lo, 1
	s_cmp_lg_u32 vcc_lo, s100
	s_cbranch_scc1 .Lfb_poll_6
	buffer_wbl2 sc1
	s_waitcnt vmcnt(0)
	s_mov_b64 exec, 0xffff
	v_mbcnt_lo_u32_b32 v255, -1, 0
	v_mov_b32_e32 v254, vcc_hi
	v_lshlrev_b32_e32 v255, 8, v255
	v_add_u32_e32 v255, 0x2400, v255
	global_atomic_add v255, v254, s[98:99]
	s_mov_b64 exec, 1

; DI unsigned xb_ld(unsigned* p) { return __hip_atomic_load(p, __ATOMIC_RELAXED, __HIP_MEMORY_SCOPE_AGENT); }
; DI unsigned xb_add(unsigned* p, unsigned v) { return __hip_atomic_fetch_add(p, v, __ATOMIC_RELAXED, __HIP_MEMORY_SCOPE_AGENT); }
; #define XB_SPIN(cond, bar) do { unsigned _sp = 0; while (cond) { __builtin_amdgcn_s_sleep(1); \
;     if ((++_sp & 255u) == 0u) { if (xb_ld(&(bar)[XB_TMO])) break; if (_sp > XB_SPIN_CAP) { atomicAdd(&(bar)[XB_TMO], 1u); break; } } } } while (0)
; DI void xcd_barrier(const XcdBarrier& b) {
;   asm volatile("s_waitcnt vmcnt(0)" ::: "memory");
;   __syncthreads();
;   if (threadIdx.x == 0) {
;     unsigned* bar = b.bar;
;     __builtin_amdgcn_s_waitcnt(0);
;     unsigned nloc = b.st[0], nx = b.st[1];
;     if (nloc == 0u) { xcd_barrier_complete(bar, b.x, nloc, nx); b.st[0] = nloc; b.st[1] = nx; }
;     const unsigned old = xb_add(&bar[XB_XSUB(b.x)], 1u);
;     const unsigned gen = old / nloc;
;     if (old + 1u == (gen + 1u) * nloc) {
;       __builtin_amdgcn_fence(__ATOMIC_RELEASE, "agent");
;       asm volatile("s_waitcnt vmcnt(0)" ::: "memory");
;       const unsigned og = xb_add(&bar[XB_TOP], 1u);
;       const unsigned tg = og / nx;
;       if (og + 1u == (tg + 1u) * nx) xb_add(&bar[XB_TOPGEN], 1u);
;       else XB_SPIN(xb_ld(&bar[XB_TOPGEN]) == tg, bar);
;       __builtin_amdgcn_fence(__ATOMIC_ACQUIRE, "agent");
;       xb_add(&bar[XB_XGEN(b.x)], 1u);
;       asm volatile("s_waitcnt vmcnt(0)" ::: "memory");
;     } else {
;       XB_SPIN(xb_ld(&bar[XB_XGEN(b.x)]) == gen, bar);
;       __builtin_amdgcn_fence(__ATOMIC_ACQUIRE, "agent");
;       asm volatile("s_waitcnt vmcnt(0)" ::: "memory");
;     }
;   }
;   __syncthreads();
; }
.LBB0_980:
	s_getreg_b32 s8, hwreg(HW_REG_XCC_ID, 0, 4)
	s_waitcnt vmcnt(0)
	s_barrier
	s_and_saveexec_b64 s[0:1], s[4:5]
	s_cbranch_execz .LBB0_1032
	v_readlane_b32 s98, v226, 47
	v_readlane_b32 s99, v226, 48
	v_readlane_b32 s101, v226, 49
	v_readlane_b32 s100, v226, 46
	v_readlane_b32 vcc_hi, v226, 50
	s_getreg_b32 vcc_lo, hwreg(HW_REG_XCC_ID, 0, 4)
	s_add_u32 s100, s100, 1
	s_lshl_b32 vcc_lo, vcc_lo, 8
	v_writelane_b32 v226, s100, 46
	s_add_u32 vcc_lo, vcc_lo, 0x1400
	s_mul_i32 s101, s101, s100
	s_mul_i32 s100, vcc_hi, s100
	v_mov_b32_e32 v253, vcc_lo
	v_mov_b32_e32 v254, 1
	global_atomic_add v254, v253, v254, s[98:99] sc0
	v_add_u32_e32 v253, 0x1000, v253
	s_waitcnt vmcnt(0)
	v_readfirstlane_b32 vcc_lo, v254
	s_add_u32 vcc_lo, vcc_lo, 1
	s_cmp_lg_u32 vcc_lo, s100
	s_cbranch_scc1 .Lfb_poll_7
	buffer_wbl2 sc1
	s_waitcnt vmcnt(0)
	s_mov_b64 exec, 0xffff
	v_mbcnt_lo_u32_b32 v255, -1, 0
	v_mov_b32_e32 v254, vcc_hi
	v_lshlrev_b32_e32 v255, 8, v255
	v_add_u32_e32 v255, 0x2400, v255
	global_atomic_add v255, v254, s[98:99]
	s_mov_b64 exec, 1

; DI unsigned xb_ld(unsigned* p) { return __hip_atomic_load(p, __ATOMIC_RELAXED, __HIP_MEMORY_SCOPE_AGENT); }
; DI unsigned xb_add(unsigned* p, unsigned v) { return __hip_atomic_fetch_add(p, v, __ATOMIC_RELAXED, __HIP_MEMORY_SCOPE_AGENT); }
; #define XB_SPIN(cond, bar) do { unsigned _sp = 0; while (cond) { __builtin_amdgcn_s_sleep(1); \
;     if ((++_sp & 255u) == 0u) { if (xb_ld(&(bar)[XB_TMO])) break; if (_sp > XB_SPIN_CAP) { atomicAdd(&(bar)[XB_TMO], 1u); break; } } } } while (0)
; DI void xcd_barrier(const XcdBarrier& b) {
;   asm volatile("s_waitcnt vmcnt(0)" ::: "memory");
;   __syncthreads();
;   if (threadIdx.x == 0) {
;     unsigned* bar = b.bar;
;     __builtin_amdgcn_s_waitcnt(0);
;     unsigned nloc = b.st[0], nx = b.st[1];
;     if (nloc == 0u) { xcd_barrier_complete(bar, b.x, nloc, nx); b.st[0] = nloc; b.st[1] = nx; }
;     const unsigned old = xb_add(&bar[XB_XSUB(b.x)], 1u);
;     const unsigned gen = old / nloc;
;     if (old + 1u == (gen + 1u) * nloc) {
;       __builtin_amdgcn_fence(__ATOMIC_RELEASE, "agent");
;       asm volatile("s_waitcnt vmcnt(0)" ::: "memory");
;       const unsigned og = xb_add(&bar[XB_TOP], 1u);
;       const unsigned tg = og / nx;
;       if (og + 1u == (tg + 1u) * nx) xb_add(&bar[XB_TOPGEN], 1u);
;       else XB_SPIN(xb_ld(&bar[XB_TOPGEN]) == tg, bar);
;       __builtin_amdgcn_fence(__ATOMIC_ACQUIRE, "agent");
;       xb_add(&bar[XB_XGEN(b.x)], 1u);
;       asm volatile("s_waitcnt vmcnt(0)" ::: "memory");
;     } else {
;       XB_SPIN(xb_ld(&bar[XB_XGEN(b.x)]) == gen, bar);
;       __builtin_amdgcn_fence(__ATOMIC_ACQUIRE, "agent");
;       asm volatile("s_waitcnt vmcnt(0)" ::: "memory");
;     }
;   }
;   __syncthreads();
; }
.LBB0_1069:
	s_getreg_b32 s2, hwreg(HW_REG_XCC_ID, 0, 4)
	s_waitcnt vmcnt(0)
	v_readlane_b32 s56, v226, 6
	v_readlane_b32 s57, v226, 7
	s_barrier
	s_and_saveexec_b64 s[0:1], s[4:5]
	v_readlane_b32 s35, v226, 3
	v_readlane_b32 s38, v226, 2
	s_cbranch_execz .LBB0_1121
	v_readlane_b32 s98, v226, 47
	v_readlane_b32 s99, v226, 48
	v_readlane_b32 s101, v226, 49
	v_readlane_b32 s100, v226, 46
	v_readlane_b32 vcc_hi, v226, 50
	s_getreg_b32 vcc_lo, hwreg(HW_REG_XCC_ID, 0, 4)
	s_add_u32 s100, s100, 1
	s_lshl_b32 vcc_lo, vcc_lo, 8
	v_writelane_b32 v226, s100, 46
	s_add_u32 vcc_lo, vcc_lo, 0x1400
	s_mul_i32 s101, s101, s100
	s_mul_i32 s100, vcc_hi, s100
	v_mov_b32_e32 v253, vcc_lo
	v_mov_b32_e32 v254, 1
	global_atomic_add v254, v253, v254, s[98:99] sc0
	v_add_u32_e32 v253, 0x1000, v253
	s_waitcnt vmcnt(0)
	v_readfirstlane_b32 vcc_lo, v254
	s_add_u32 vcc_lo, vcc_lo, 1
	s_cmp_lg_u32 vcc_lo, s100
	s_cbranch_scc1 .Lfb_poll_8
	buffer_wbl2 sc1
	s_waitcnt vmcnt(0)
	s_mov_b64 exec, 0xffff
	v_mbcnt_lo_u32_b32 v255, -1, 0
	v_mov_b32_e32 v254, vcc_hi
	v_lshlrev_b32_e32 v255, 8, v255
	v_add_u32_e32 v255, 0x2400, v255
	global_atomic_add v255, v254, s[98:99]
	s_mov_b64 exec, 1

; DI unsigned xb_ld(unsigned* p) { return __hip_atomic_load(p, __ATOMIC_RELAXED, __HIP_MEMORY_SCOPE_AGENT); }
; DI unsigned xb_add(unsigned* p, unsigned v) { return __hip_atomic_fetch_add(p, v, __ATOMIC_RELAXED, __HIP_MEMORY_SCOPE_AGENT); }
; #define XB_SPIN(cond, bar) do { unsigned _sp = 0; while (cond) { __builtin_amdgcn_s_sleep(1); \
;     if ((++_sp & 255u) == 0u) { if (xb_ld(&(bar)[XB_TMO])) break; if (_sp > XB_SPIN_CAP) { atomicAdd(&(bar)[XB_TMO], 1u); break; } } } } while (0)
; DI void xcd_barrier(const XcdBarrier& b) {
;   asm volatile("s_waitcnt vmcnt(0)" ::: "memory");
;   __syncthreads();
;   if (threadIdx.x == 0) {
;     unsigned* bar = b.bar;
;     __builtin_amdgcn_s_waitcnt(0);
;     unsigned nloc = b.st[0], nx = b.st[1];
;     if (nloc == 0u) { xcd_barrier_complete(bar, b.x, nloc, nx); b.st[0] = nloc; b.st[1] = nx; }
;     const unsigned old = xb_add(&bar[XB_XSUB(b.x)], 1u);
;     const unsigned gen = old / nloc;
;     if (old + 1u == (gen + 1u) * nloc) {
;       __builtin_amdgcn_fence(__ATOMIC_RELEASE, "agent");
;       asm volatile("s_waitcnt vmcnt(0)" ::: "memory");
;       const unsigned og = xb_add(&bar[XB_TOP], 1u);
;       const unsigned tg = og / nx;
;       if (og + 1u == (tg + 1u) * nx) xb_add(&bar[XB_TOPGEN], 1u);
;       else XB_SPIN(xb_ld(&bar[XB_TOPGEN]) == tg, bar);
;       __builtin_amdgcn_fence(__ATOMIC_ACQUIRE, "agent");
;       xb_add(&bar[XB_XGEN(b.x)], 1u);
;       asm volatile("s_waitcnt vmcnt(0)" ::: "memory");
;     } else {
;       XB_SPIN(xb_ld(&bar[XB_XGEN(b.x)]) == gen, bar);
;       __builtin_amdgcn_fence(__ATOMIC_ACQUIRE, "agent");
;       asm volatile("s_waitcnt vmcnt(0)" ::: "memory");
;     }
;   }
;   __syncthreads();
; }
.LBB0_1210:
	s_getreg_b32 s12, hwreg(HW_REG_XCC_ID, 0, 4)
	s_waitcnt vmcnt(0)
	s_barrier
	s_and_saveexec_b64 s[0:1], s[4:5]
	s_cbranch_execz .LBB0_1262
	v_readlane_b32 s98, v226, 47
	v_readlane_b32 s99, v226, 48
	v_readlane_b32 s101, v226, 49
	v_readlane_b32 s100, v226, 46
	v_readlane_b32 vcc_hi, v226, 50
	s_getreg_b32 vcc_lo, hwreg(HW_REG_XCC_ID, 0, 4)
	s_add_u32 s100, s100, 1
	s_lshl_b32 vcc_lo, vcc_lo, 8
	v_writelane_b32 v226, s100, 46
	s_add_u32 vcc_lo, vcc_lo, 0x1400
	s_mul_i32 s101, s101, s100
	s_mul_i32 s100, vcc_hi, s100
	v_mov_b32_e32 v253, vcc_lo
	v_mov_b32_e32 v254, 1
	global_atomic_add v254, v253, v254, s[98:99] sc0
	v_add_u32_e32 v253, 0x1000, v253
	s_waitcnt vmcnt(0)
	v_readfirstlane_b32 vcc_lo, v254
	s_add_u32 vcc_lo, vcc_lo, 1
	s_cmp_lg_u32 vcc_lo, s100
	s_cbranch_scc1 .Lfb_poll_10
	buffer_wbl2 sc1
	s_waitcnt vmcnt(0)
	s_mov_b64 exec, 0xffff
	v_mbcnt_lo_u32_b32 v255, -1, 0
	v_mov_b32_e32 v254, vcc_hi
	v_lshlrev_b32_e32 v255, 8, v255
	v_add_u32_e32 v255, 0x2400, v255
	global_atomic_add v255, v254, s[98:99]
	s_mov_b64 exec, 1

; DI unsigned xb_ld(unsigned* p) { return __hip_atomic_load(p, __ATOMIC_RELAXED, __HIP_MEMORY_SCOPE_AGENT); }
; DI unsigned xb_add(unsigned* p, unsigned v) { return __hip_atomic_fetch_add(p, v, __ATOMIC_RELAXED, __HIP_MEMORY_SCOPE_AGENT); }
; #define XB_SPIN(cond, bar) do { unsigned _sp = 0; while (cond) { __builtin_amdgcn_s_sleep(1); \
;     if ((++_sp & 255u) == 0u) { if (xb_ld(&(bar)[XB_TMO])) break; if (_sp > XB_SPIN_CAP) { atomicAdd(&(bar)[XB_TMO], 1u); break; } } } } while (0)
; DI void xcd_barrier(const XcdBarrier& b) {
;   asm volatile("s_waitcnt vmcnt(0)" ::: "memory");
;   __syncthreads();
;   if (threadIdx.x == 0) {
;     unsigned* bar = b.bar;
;     __builtin_amdgcn_s_waitcnt(0);
;     unsigned nloc = b.st[0], nx = b.st[1];
;     if (nloc == 0u) { xcd_barrier_complete(bar, b.x, nloc, nx); b.st[0] = nloc; b.st[1] = nx; }
;     const unsigned old = xb_add(&bar[XB_XSUB(b.x)], 1u);
;     const unsigned gen = old / nloc;
;     if (old + 1u == (gen + 1u) * nloc) {
;       __builtin_amdgcn_fence(__ATOMIC_RELEASE, "agent");
;       asm volatile("s_waitcnt vmcnt(0)" ::: "memory");
;       const unsigned og = xb_add(&bar[XB_TOP], 1u);
;       const unsigned tg = og / nx;
;       if (og + 1u == (tg + 1u) * nx) xb_add(&bar[XB_TOPGEN], 1u);
;       else XB_SPIN(xb_ld(&bar[XB_TOPGEN]) == tg, bar);
;       __builtin_amdgcn_fence(__ATOMIC_ACQUIRE, "agent");
;       xb_add(&bar[XB_XGEN(b.x)], 1u);
;       asm volatile("s_waitcnt vmcnt(0)" ::: "memory");
;     } else {
;       XB_SPIN(xb_ld(&bar[XB_XGEN(b.x)]) == gen, bar);
;       __builtin_amdgcn_fence(__ATOMIC_ACQUIRE, "agent");
;       asm volatile("s_waitcnt vmcnt(0)" ::: "memory");
;     }
;   }
;   __syncthreads();
; }
.LBB0_1444:
	s_or_b64 exec, exec, s[24:25]
	s_getreg_b32 s2, hwreg(HW_REG_XCC_ID, 0, 4)
	s_waitcnt vmcnt(0)
	s_barrier
	s_and_saveexec_b64 s[0:1], s[4:5]
	s_cbranch_execz .LBB0_1496
	v_readlane_b32 s98, v226, 47
	v_readlane_b32 s99, v226, 48
	v_readlane_b32 s101, v226, 49
	v_readlane_b32 s100, v226, 46
	v_readlane_b32 vcc_hi, v226, 50
	s_getreg_b32 vcc_lo, hwreg(HW_REG_XCC_ID, 0, 4)
	s_add_u32 s100, s100, 1
	s_lshl_b32 vcc_lo, vcc_lo, 8
	v_writelane_b32 v226, s100, 46
	s_add_u32 vcc_lo, vcc_lo, 0x1400
	s_mul_i32 s101, s101, s100
	s_mul_i32 s100, vcc_hi, s100
	v_mov_b32_e32 v253, vcc_lo
	v_mov_b32_e32 v254, 1
	global_atomic_add v254, v253, v254, s[98:99] sc0
	v_add_u32_e32 v253, 0x1000, v253
	s_waitcnt vmcnt(0)
	v_readfirstlane_b32 vcc_lo, v254
	s_add_u32 vcc_lo, vcc_lo, 1
	s_cmp_lg_u32 vcc_lo, s100
	s_cbranch_scc1 .Lfb_poll_13
	buffer_wbl2 sc1
	s_waitcnt vmcnt(0)
	s_mov_b64 exec, 0xffff
	v_mbcnt_lo_u32_b32 v255, -1, 0
	v_mov_b32_e32 v254, vcc_hi
	v_lshlrev_b32_e32 v255, 8, v255
	v_add_u32_e32 v255, 0x2400, v255
	global_atomic_add v255, v254, s[98:99]
	s_mov_b64 exec, 1
